# split-barrier seams in P8: first poll load issued together with the arrival atomic (one round trip instead of two)
# speedup vs baseline: 1.0080x; 1.0041x over previous
.LBB0_1064:
	s_waitcnt vmcnt(0)
	s_waitcnt lgkmcnt(0)
	s_barrier
	s_and_saveexec_b64 s[10:11], s[92:93]
	s_cbranch_execz .LBB0_1116
	v_mov_b32_e32 v2, 0x22000
	ds_read_b64 v[4:5], v2
	s_lshl_b32 s0, s87, 8
	s_add_i32 s0, s0, 0x2b5d048
	v_mov_b32_e32 v2, s0
	v_mov_b32_e32 v3, 1
	global_atomic_add v6, v2, v3, s[88:89] sc0
	v_mov_b32_e32 v7, 0x2b5d044
	global_load_dword v8, v7, s[88:89] sc1
	s_waitcnt vmcnt(0) lgkmcnt(0)
	v_add_u32_e32 v6, 1, v6
	v_cmp_eq_u32_e32 vcc, v6, v4
	s_cbranch_vccz .Lp8s_notlast
	buffer_wbl2 sc1
	s_waitcnt vmcnt(0)
	v_mov_b32_e32 v2, 0x2b5d04c
	global_atomic_add v2, v3, s[88:89]
.Lp8s_notlast:
	v_mov_b32_e32 v2, 0x2b5d044
	s_mov_b32 s1, 0x100000
	v_cmp_ge_u32_e32 vcc, v8, v5
	s_cbranch_vccnz .Lp8s_done

.LBB0_1125:
	s_or_b64 exec, exec, s[18:19]
	s_waitcnt vmcnt(0)
	s_barrier
	s_and_saveexec_b64 s[100:101], s[92:93]
	s_cbranch_execz .Lp8c_out
	v_mov_b32_e32 v2, 0x22000
	ds_read_b32 v4, v2
	s_lshl_b32 s0, s87, 8
	s_add_i32 s0, s0, 0x2b5d034
	v_mov_b32_e32 v2, s0
	v_mov_b32_e32 v3, 1
	global_atomic_add v6, v2, v3, s[88:89] sc0
	v_mov_b32_e32 v7, 0x2b5d04c
	global_load_dword v8, v7, s[88:89] sc1
	v_mov_b32_e32 v7, 0x22004
	ds_read_b32 v9, v7
	s_waitcnt vmcnt(0) lgkmcnt(0)
	v_add_u32_e32 v6, 1, v6
	v_cmp_eq_u32_e32 vcc, v6, v4
	s_cbranch_vccz .Lp8c_end
	buffer_wbl2 sc1
	s_waitcnt vmcnt(0)
	v_mov_b32_e32 v2, 0x2b5d038
	global_atomic_add v2, v3, s[88:89]
.Lp8c_end:
	v_mov_b32_e32 v2, 0x22004
	ds_read_b32 v4, v2
	v_mov_b32_e32 v2, 0x2b5d04c
	s_mov_b32 s1, 0x100000
	s_waitcnt lgkmcnt(0)
	v_cmp_ge_u32_e32 vcc, v8, v9
	s_cbranch_vccnz .Lp8x_done
